# v64 + nt on the P5 residual-epilogue f32 base loads (last use of the input)
# speedup vs baseline: 1.0004x; 1.0004x over previous
.LBB0_633:
	v_lshl_or_b32 v192, s8, 8, v208
	v_lshl_add_u32 v196, s49, 8, v206
	v_ashrrev_i32_e32 v193, 31, v192
	v_ashrrev_i32_e32 v197, 31, v196
	v_lshl_add_u64 v[194:195], v[192:193], 2, s[56:57]
	v_lshlrev_b64 v[128:129], 12, v[196:197]
	v_lshl_add_u64 v[128:129], v[194:195], 0, v[128:129]
	global_load_dwordx4 v[214:217], v[128:129], off nt
	global_load_dwordx4 v[218:221], v[128:129], off offset:16 nt
	global_load_dwordx4 v[222:225], v[128:129], off offset:512 nt
	global_load_dwordx4 v[226:229], v[128:129], off offset:528 nt
	v_or_b32_e32 v202, 16, v196
	v_or_b32_e32 v200, 32, v196
	v_or_b32_e32 v198, 48, v196
	v_ashrrev_i32_e32 v203, 31, v202
	v_ashrrev_i32_e32 v201, 31, v200
	v_ashrrev_i32_e32 v199, 31, v198
	v_lshlrev_b64 v[128:129], 12, v[202:203]
	v_lshlrev_b64 v[130:131], 12, v[200:201]
	v_lshlrev_b64 v[132:133], 12, v[198:199]
	v_lshl_add_u64 v[128:129], v[194:195], 0, v[128:129]
	v_lshl_add_u64 v[130:131], v[194:195], 0, v[130:131]
	v_lshl_add_u64 v[132:133], v[194:195], 0, v[132:133]
	global_load_dwordx4 v[168:171], v[128:129], off offset:16 nt
	global_load_dwordx4 v[172:175], v[128:129], off nt
	global_load_dwordx4 v[160:163], v[128:129], off offset:528 nt
	global_load_dwordx4 v[164:167], v[128:129], off offset:512 nt
	global_load_dwordx4 v[152:155], v[130:131], off offset:16 nt
	global_load_dwordx4 v[156:159], v[130:131], off nt
	global_load_dwordx4 v[144:147], v[130:131], off offset:528 nt
	global_load_dwordx4 v[148:151], v[130:131], off offset:512 nt
	global_load_dwordx4 v[136:139], v[132:133], off offset:16 nt
	global_load_dwordx4 v[140:143], v[132:133], off nt
	s_nop 0
	global_load_dwordx4 v[128:131], v[132:133], off offset:528 nt
	s_nop 0
	global_load_dwordx4 v[132:135], v[132:133], off offset:512 nt
	v_lshlrev_b64 v[230:231], 11, v[196:197]
	v_lshl_add_u64 v[230:231], s[58:59], 0, v[230:231]
	v_lshl_add_u64 v[230:231], v[192:193], 1, v[230:231]
	s_lshl_b32 s4, s8, 2
	s_ashr_i32 s5, s4, 31
	s_waitcnt vmcnt(0)
	v_pk_add_f32 v[126:127], v[126:127], v[216:217]
	v_pk_add_f32 v[124:125], v[124:125], v[214:215]
	v_pk_add_f32 v[122:123], v[122:123], v[220:221]
	v_pk_add_f32 v[120:121], v[120:121], v[218:219]
	v_pk_add_f32 v[216:217], v[112:113], v[226:227]
	v_cvt_pk_bf16_f32 v112, v124, v125
	v_cvt_pk_bf16_f32 v113, v126, v127
	v_pk_add_f32 v[118:119], v[118:119], v[224:225]
	v_pk_add_f32 v[116:117], v[116:117], v[222:223]
	v_pk_add_f32 v[214:215], v[114:115], v[228:229]
	v_cvt_pk_bf16_f32 v114, v120, v121
	v_cvt_pk_bf16_f32 v115, v122, v123
	global_store_dwordx4 v[230:231], v[112:115], off
	v_lshlrev_b32_e32 v120, 16, v112
	v_lshlrev_b32_e32 v121, 16, v113
	v_and_b32_e32 v112, 0xffff0000, v112
	v_and_b32_e32 v113, 0xffff0000, v113
	v_and_b32_e32 v123, 0xffff0000, v114
	v_and_b32_e32 v125, 0xffff0000, v115
	v_lshlrev_b32_e32 v122, 16, v114
	v_lshlrev_b32_e32 v124, 16, v115
	v_cvt_pk_bf16_f32 v114, v116, v117
	v_cvt_pk_bf16_f32 v115, v118, v119
	v_cvt_pk_bf16_f32 v116, v216, v217
	v_cvt_pk_bf16_f32 v117, v214, v215
	v_mul_f32_e32 v112, v112, v112
	v_mul_f32_e32 v113, v113, v113
	v_mul_f32_e32 v118, v123, v123
	v_mul_f32_e32 v119, v125, v125
	v_and_b32_e32 v125, 0xffff0000, v114
	v_and_b32_e32 v127, 0xffff0000, v115
	v_and_b32_e32 v214, 0xffff0000, v116
	v_and_b32_e32 v216, 0xffff0000, v117
	v_lshlrev_b32_e32 v123, 16, v114
	v_lshlrev_b32_e32 v126, 16, v115
	v_lshlrev_b32_e32 v213, 16, v116
	v_lshlrev_b32_e32 v215, 16, v117
	v_fmac_f32_e32 v112, v120, v120
	v_fmac_f32_e32 v113, v121, v121
	v_fmac_f32_e32 v118, v122, v122
	v_fmac_f32_e32 v119, v124, v124
	v_mul_f32_e32 v120, v125, v125
	v_mul_f32_e32 v121, v127, v127
	v_mul_f32_e32 v122, v214, v214
	v_mul_f32_e32 v124, v216, v216
	v_add_f32_e32 v112, v112, v113
	v_add_f32_e32 v113, v118, v119
	v_fmac_f32_e32 v120, v123, v123
	v_fmac_f32_e32 v121, v126, v126
	v_fmac_f32_e32 v122, v213, v213
	v_fmac_f32_e32 v124, v215, v215
	v_add_f32_e32 v112, v112, v113
	v_add_f32_e32 v113, v120, v121
	v_add_f32_e32 v118, v122, v124
	v_add_f32_e32 v113, v113, v118
	v_and_b32_e32 v118, 64, v212
	v_add_f32_e32 v112, v112, v113
	v_xor_b32_e32 v113, 16, v212
	v_add_u32_e32 v118, 64, v118
	v_cmp_lt_i32_e32 vcc, v113, v118
	global_store_dwordx4 v[230:231], v[114:117], off offset:256
	s_nop 0
	v_cndmask_b32_e32 v113, v212, v113, vcc
	v_lshlrev_b32_e32 v120, 2, v113
	ds_bpermute_b32 v113, v120, v112
	s_waitcnt lgkmcnt(0)
	v_add_f32_e32 v112, v112, v113
	v_xor_b32_e32 v113, 32, v212
	v_cmp_lt_i32_e32 vcc, v113, v118
	s_nop 1
	v_cndmask_b32_e32 v113, v212, v113, vcc
	v_lshlrev_b32_e32 v121, 2, v113
	ds_bpermute_b32 v113, v121, v112
	s_and_saveexec_b64 s[24:25], s[0:1]
	s_cbranch_execz .LBB0_635
	v_lshlrev_b64 v[114:115], 6, v[196:197]
	v_lshl_add_u64 v[114:115], s[62:63], 0, v[114:115]
	v_lshl_add_u64 v[114:115], s[4:5], 2, v[114:115]
	s_lshl_b32 s8, s41, 2
	v_lshl_add_u64 v[114:115], v[114:115], 0, s[8:9]
	s_waitcnt lgkmcnt(0)
	v_add_f32_e32 v112, v112, v113
	global_store_dword v[114:115], v112, off

.LBB0_641:
	s_or_b64 exec, exec, s[24:25]
	v_add_u32_e32 v118, 0x80, v196
	v_ashrrev_i32_e32 v119, 31, v118
	s_waitcnt lgkmcnt(0)
	v_lshlrev_b64 v[64:65], 12, v[118:119]
	v_lshl_add_u64 v[64:65], v[194:195], 0, v[64:65]
	global_load_dwordx4 v[122:125], v[64:65], off nt
	global_load_dwordx4 v[126:129], v[64:65], off offset:16 nt
	global_load_dwordx4 v[130:133], v[64:65], off offset:512 nt
	global_load_dwordx4 v[134:137], v[64:65], off offset:528 nt
	v_add_u32_e32 v116, 0x90, v196
	v_add_u32_e32 v114, 0xa0, v196
	v_add_u32_e32 v112, 0xb0, v196
	v_ashrrev_i32_e32 v117, 31, v116
	v_ashrrev_i32_e32 v115, 31, v114
	v_ashrrev_i32_e32 v113, 31, v112
	v_lshlrev_b64 v[64:65], 12, v[116:117]
	v_lshlrev_b64 v[66:67], 12, v[114:115]
	v_lshlrev_b64 v[68:69], 12, v[112:113]
	v_lshl_add_u64 v[64:65], v[194:195], 0, v[64:65]
	v_lshl_add_u64 v[66:67], v[194:195], 0, v[66:67]
	v_lshl_add_u64 v[68:69], v[194:195], 0, v[68:69]
	global_load_dwordx4 v[104:107], v[64:65], off offset:16 nt
	global_load_dwordx4 v[108:111], v[64:65], off nt
	global_load_dwordx4 v[96:99], v[64:65], off offset:528 nt
	global_load_dwordx4 v[100:103], v[64:65], off offset:512 nt
	global_load_dwordx4 v[88:91], v[66:67], off offset:16 nt
	global_load_dwordx4 v[92:95], v[66:67], off nt
	global_load_dwordx4 v[80:83], v[66:67], off offset:528 nt
	global_load_dwordx4 v[84:87], v[66:67], off offset:512 nt
	global_load_dwordx4 v[72:75], v[68:69], off offset:16 nt
	global_load_dwordx4 v[76:79], v[68:69], off nt
	s_nop 0
	global_load_dwordx4 v[64:67], v[68:69], off offset:528 nt
	s_nop 0
	global_load_dwordx4 v[68:71], v[68:69], off offset:512 nt
	v_lshlrev_b64 v[138:139], 11, v[118:119]
	v_lshl_add_u64 v[138:139], s[58:59], 0, v[138:139]
	v_lshl_add_u64 v[138:139], v[192:193], 1, v[138:139]
	s_waitcnt vmcnt(15)
	v_pk_add_f32 v[62:63], v[62:63], v[124:125]
	v_pk_add_f32 v[60:61], v[60:61], v[122:123]
	s_waitcnt vmcnt(14)
	v_pk_add_f32 v[58:59], v[58:59], v[128:129]
	v_pk_add_f32 v[56:57], v[56:57], v[126:127]
	s_waitcnt vmcnt(12)
	v_pk_add_f32 v[124:125], v[48:49], v[134:135]
	v_cvt_pk_bf16_f32 v48, v60, v61
	v_cvt_pk_bf16_f32 v49, v62, v63
	v_pk_add_f32 v[54:55], v[54:55], v[132:133]
	v_pk_add_f32 v[52:53], v[52:53], v[130:131]
	v_pk_add_f32 v[122:123], v[50:51], v[136:137]
	v_cvt_pk_bf16_f32 v50, v56, v57
	v_cvt_pk_bf16_f32 v51, v58, v59
	global_store_dwordx4 v[138:139], v[48:51], off
	v_lshlrev_b32_e32 v56, 16, v48
	v_lshlrev_b32_e32 v57, 16, v49
	v_and_b32_e32 v48, 0xffff0000, v48
	v_and_b32_e32 v49, 0xffff0000, v49
	v_and_b32_e32 v59, 0xffff0000, v50
	v_and_b32_e32 v61, 0xffff0000, v51
	v_lshlrev_b32_e32 v58, 16, v50
	v_lshlrev_b32_e32 v60, 16, v51
	v_cvt_pk_bf16_f32 v50, v52, v53
	v_cvt_pk_bf16_f32 v51, v54, v55
	v_cvt_pk_bf16_f32 v52, v124, v125
	v_cvt_pk_bf16_f32 v53, v122, v123
	v_mul_f32_e32 v48, v48, v48
	v_mul_f32_e32 v49, v49, v49
	v_mul_f32_e32 v54, v59, v59
	v_mul_f32_e32 v55, v61, v61
	v_and_b32_e32 v61, 0xffff0000, v50
	v_and_b32_e32 v63, 0xffff0000, v51
	v_and_b32_e32 v123, 0xffff0000, v52
	v_and_b32_e32 v125, 0xffff0000, v53
	v_lshlrev_b32_e32 v59, 16, v50
	v_lshlrev_b32_e32 v62, 16, v51
	v_lshlrev_b32_e32 v122, 16, v52
	v_lshlrev_b32_e32 v124, 16, v53
	v_fmac_f32_e32 v48, v56, v56
	v_fmac_f32_e32 v49, v57, v57
	v_fmac_f32_e32 v54, v58, v58
	v_fmac_f32_e32 v55, v60, v60
	v_mul_f32_e32 v56, v61, v61
	v_mul_f32_e32 v57, v63, v63
	v_mul_f32_e32 v58, v123, v123
	v_mul_f32_e32 v60, v125, v125
	v_add_f32_e32 v48, v48, v49
	v_add_f32_e32 v49, v54, v55
	v_fmac_f32_e32 v56, v59, v59
	v_fmac_f32_e32 v57, v62, v62
	v_fmac_f32_e32 v58, v122, v122
	v_fmac_f32_e32 v60, v124, v124
	v_add_f32_e32 v48, v48, v49
	v_add_f32_e32 v49, v56, v57
	v_add_f32_e32 v54, v58, v60
	v_add_f32_e32 v49, v49, v54
	v_add_f32_e32 v48, v48, v49
	ds_bpermute_b32 v49, v120, v48
	global_store_dwordx4 v[138:139], v[50:53], off offset:256
	s_waitcnt lgkmcnt(0)
	v_add_f32_e32 v48, v48, v49
	ds_bpermute_b32 v49, v121, v48
	s_and_saveexec_b64 s[24:25], s[0:1]
	s_cbranch_execz .LBB0_643
	v_lshlrev_b64 v[50:51], 6, v[118:119]
	v_lshl_add_u64 v[50:51], s[62:63], 0, v[50:51]
	v_lshl_add_u64 v[50:51], s[4:5], 2, v[50:51]
	s_lshl_b32 s8, s41, 2
	v_lshl_add_u64 v[50:51], v[50:51], 0, s[8:9]
	s_waitcnt lgkmcnt(0)
	v_add_f32_e32 v48, v48, v49
	global_store_dword v[50:51], v48, off
